# loop-edge rotation of the attention tile loop (next tile LDS read bases formed before the tile barrier, common path falls through) plus pipelined meta-row GEMM K loop
# speedup vs baseline: 1.0090x; 1.0016x over previous
; #define LAS __attribute__((address_space(3)))
; __device__ __forceinline__ int v_rd_base(int lane) { return ((lane & 3) << 3) | (((lane >> 2) & 3) << 6) | (((lane >> 4) & 1) << 5) | (((lane >> 5) & 1) << 8); }
; __device__ __forceinline__ void attn_unit(const bf16_t* __restrict__ Qb, const bf16_t* __restrict__ Kh, const bf16_t* __restrict__ Vh, bf16_t* __restrict__ Ob,
;                                           LAS unsigned char* lds, float MB, int tid, int nrows, int t0, int t1, float* part, float* partl) {
;     ...
;     float l_reg = 0.f; f32x16 o[4] = {}; bf16x8 qr[QREG];
;     LAS unsigned char* qt = lds + LDS_QT + wid * ((12 - QREG) * 1024) + lane * 16;
;     const unsigned qo = (unsigned)((wid * 32 + r32) * LDQ + hi * 8) * 2u;
; #pragma unroll
;     for (int d0 = 0; d0 < QREG; ++d0) qr[d0] = *(const bf16x8*)((const char*)Qb + qo + d0 * 32);
; #pragma unroll
;     for (int d0 = QREG; d0 < 12; ++d0) *(LAS bf16x8*)(qt + (d0 - QREG) * 1024) = *(const bf16x8*)((const char*)Qb + qo + d0 * 32);
;     unsigned ko[3], vo[2];
; #pragma unroll
;     for (int i = 0; i < 3; ++i) { const int sl = tid + 512 * i, row = sl / 24, pc = sl - row * 24, ch = pc ^ ((row >> 1) & 7); ko[i] = (unsigned)(row * LDKK + ch * 8) * 2u; }
; #pragma unroll
;     for (int i = 0; i < 2; ++i) { const int sl = tid + 512 * i, sub = sl >> 5, kk = (sub >> 2) * 8 + ((sl >> 2) & 7), c = (sub & 3) * 32 + (sl & 3) * 8;
;         const int kx = (kk & ~0xC) | ((kk & 4) << 1) | ((kk & 8) >> 1); vo[i] = (unsigned)(kx * LDV + c) * 2u; }
;     const int vb0 = (int)(unsigned)(uintptr_t)V_lds + v_rd_base(lane);
;     const unsigned ldw = (unsigned)wid * 1024u;
;     ...
;     f32x16 p0, p1; bf16x8 pa0, pa1, pa2, pa3;
;     SDMA(t0 * KVBLK, 0); asm volatile("s_waitcnt vmcnt(0)" ::: "memory"); __syncthreads();
.LBB0_136:
	v_mov_b32_e32 v147, v221
	v_mov_b32_e32 v213, v209
	v_mov_b32_e32 v214, v210
	s_mov_b32 s65, 0
	v_mov_b32_e32 v155, 0
	v_mov_b32_e32 v149, 0
	s_add_i32 s61, s58, 0x4000
	s_add_i32 s62, s58, 0x10000
	s_add_i32 s63, s58, 0x12000
	s_add_i32 s52, s52, 64
	s_mov_b32 s64, 0
	v_mov_b32_e32 v48, 0
	v_mov_b32_e32 v49, v155
	v_mov_b32_e32 v50, v155
	v_mov_b32_e32 v51, v155
	v_mov_b32_e32 v52, v155
	v_mov_b32_e32 v53, v155
	v_mov_b32_e32 v54, v155
	v_mov_b32_e32 v55, v155
	v_mov_b32_e32 v56, v155
	v_mov_b32_e32 v57, v155
	v_mov_b32_e32 v58, v155
	v_mov_b32_e32 v59, v155
	v_mov_b32_e32 v60, v155
	v_mov_b32_e32 v61, v155
	v_mov_b32_e32 v62, v155
	v_mov_b32_e32 v63, v155
	v_mov_b32_e32 v32, 0
	v_mov_b32_e32 v33, v155
	v_mov_b32_e32 v34, v155
	v_mov_b32_e32 v35, v155
	v_mov_b32_e32 v36, v155
	v_mov_b32_e32 v37, v155
	v_mov_b32_e32 v38, v155
	v_mov_b32_e32 v39, v155
	v_mov_b32_e32 v40, v155
	v_mov_b32_e32 v41, v155
	v_mov_b32_e32 v42, v155
	v_mov_b32_e32 v43, v155
	v_mov_b32_e32 v44, v155
	v_mov_b32_e32 v45, v155
	v_mov_b32_e32 v46, v155
	v_mov_b32_e32 v47, v155
	v_mov_b32_e32 v16, 0
	v_mov_b32_e32 v17, v155
	v_mov_b32_e32 v18, v155
	v_mov_b32_e32 v19, v155
	v_mov_b32_e32 v20, v155
	v_mov_b32_e32 v21, v155
	v_mov_b32_e32 v22, v155
	v_mov_b32_e32 v23, v155
	v_mov_b32_e32 v24, v155
	v_mov_b32_e32 v25, v155
	v_mov_b32_e32 v26, v155
	v_mov_b32_e32 v27, v155
	v_mov_b32_e32 v28, v155
	v_mov_b32_e32 v29, v155
	v_mov_b32_e32 v30, v155
	v_mov_b32_e32 v31, v155
	v_mov_b32_e32 v0, 0
	v_mov_b32_e32 v1, v155
	v_mov_b32_e32 v2, v155
	v_mov_b32_e32 v3, v155
	v_mov_b32_e32 v4, v155
	v_mov_b32_e32 v5, v155
	v_mov_b32_e32 v6, v155
	v_mov_b32_e32 v7, v155
	v_mov_b32_e32 v8, v155
	v_mov_b32_e32 v9, v155
	v_mov_b32_e32 v10, v155
	v_mov_b32_e32 v11, v155
	v_mov_b32_e32 v12, v155
	v_mov_b32_e32 v13, v155
	v_mov_b32_e32 v14, v155
	v_mov_b32_e32 v15, v155
	s_branch .LBB0_138

; #define SBAR() __builtin_amdgcn_sched_barrier(0)
; __device__ __forceinline__ void attn_unit(const bf16_t* __restrict__ Qb, const bf16_t* __restrict__ Kh, const bf16_t* __restrict__ Vh, bf16_t* __restrict__ Ob,
;                                           LAS unsigned char* lds, float MB, int tid, int nrows, int t0, int t1, float* part, float* partl) {
;     ...
;     f32x16 p0, p1; bf16x8 pa0, pa1, pa2, pa3;
;     SDMA(t0 * KVBLK, 0); asm volatile("s_waitcnt vmcnt(0)" ::: "memory"); __syncthreads();
;     for (int j = t0; j < t1; ++j) {
;         const int b = (j - t0) & 1; const bool more = (j + 1 < t1);
;         if (more) { if (b) SDMA((j + 1) * KVBLK, 0); else SDMA((j + 1) * KVBLK, 1); }
;         if (act) {
;         SBAR(); qkt(p0, p1, K_lds + b * SHM_K, qr, qt, r32, hi);
;         expP(p0, p1, MB);
;         if (j == NT - 1) maskLast(p0, p1);
;         finishP(p0, p1, l_reg, pa0, pa1, pa2, pa3); SBAR();
;         pv_d0(o, vb0 + b * SHM_V, pa0, pa1, pa2, pa3);
.Latt_w1:
	s_add_i32 s65, s65, 1
	s_cmp_eq_u32 s65, 3
	s_cselect_b32 s65, 0, s65
	s_mul_i32 s43, s65, 0x6000
	s_cmp_eq_u32 s65, 2
	s_cselect_b32 s67, 0x5000, 0
	s_cselect_b32 s69, 0xd000, 0
	s_add_i32 s43, s43, s67
	s_lshl_b32 s67, s65, 14
	s_add_i32 s69, s69, s67
	v_add_u32_e32 v147, s69, v221
	v_add_u32_e32 v213, s43, v209
	v_add_u32_e32 v214, s43, v210
	s_add_i32 s64, s64, 1
	s_add_i32 s52, s52, 64
	s_add_i32 s42, s46, s64
	s_cmp_ge_i32 s42, s47
	s_waitcnt lgkmcnt(0)
	s_barrier
	s_cbranch_scc1 .LBB0_142
.LBB0_138:
	s_add_i32 s66, s46, s64
	s_cmp_eq_u32 s64, 0
	s_cbranch_scc1 .Latt_first
.Latt_st2:
	s_andn2_b64 vcc, exec, s[50:51]
	s_cbranch_vccnz .Latt_inactive
	ds_read_b128 v[216:219], v213 offset:32768
	ds_read_b128 v[224:227], v214 offset:32768
	ds_read_b128 v[240:243], v213 offset:32896
	ds_read_b128 v[244:247], v214 offset:32896
	v_readfirstlane_b32 s70, v206
	s_nop 3
	s_cmpk_eq_i32 s66, 0x80
	s_cselect_b32 s66, 0x7f800000, s70
	s_add_i32 s67, s52, 64
	s_lshl_b32 s68, s67, 13
	s_mov_b32 s69, 0
	s_mul_i32 s43, s67, 0x1800
	s_add_u32 s70, s54, s43
	s_addc_u32 s71, s55, 0
	s_add_u32 s68, s56, s68
	s_addc_u32 s69, s57, s69
	s_add_i32 s53, s65, 2
	s_cmp_ge_u32 s53, 3
	s_cselect_b32 s42, 3, 0
	s_sub_i32 s53, s53, s42
	s_cmp_eq_u32 s53, 2
	s_cselect_b32 s42, 0x5000, 0
	s_cselect_b32 s43, 0xd000, 0
	s_mul_i32 s67, s53, 0x6000
	s_add_i32 s42, s42, s67
	s_add_i32 s42, s42, 0x8000
	s_add_i32 s42, s58, s42
	s_lshl_b32 s67, s53, 14
	s_add_i32 s43, s43, s67
	s_add_i32 s43, s58, s43
	s_waitcnt lgkmcnt(3)
	v_mfma_f32_16x16x32_bf16 v[64:67], v[216:219], v[96:99], 0
	v_mfma_f32_16x16x32_bf16 v[72:75], v[216:219], v[120:123], 0
	ds_read_b128 v[216:219], v213 offset:33024
	s_waitcnt lgkmcnt(3)
	v_mfma_f32_16x16x32_bf16 v[64:67], v[224:227], v[100:103], v[64:67]
	v_mfma_f32_16x16x32_bf16 v[72:75], v[224:227], v[124:127], v[72:75]
	ds_read_b128 v[224:227], v214 offset:33024
	s_waitcnt lgkmcnt(3)
	v_mfma_f32_16x16x32_bf16 v[64:67], v[240:243], v[104:107], v[64:67]
	v_lshl_add_u64 v[166:167], s[70:71], 0, v[156:157]
	s_mov_b32 m0, s42
	s_nop 0
	global_load_lds_dwordx4 v[166:167], off
	v_mfma_f32_16x16x32_bf16 v[72:75], v[240:243], v[128:131], v[72:75]
	ds_read_b128 v[240:243], v213 offset:38912
	s_waitcnt lgkmcnt(3)
	v_mfma_f32_16x16x32_bf16 v[64:67], v[244:247], v[108:111], v[64:67]
	v_mfma_f32_16x16x32_bf16 v[72:75], v[244:247], v[132:135], v[72:75]
	ds_read_b128 v[244:247], v214 offset:38912
	s_waitcnt lgkmcnt(3)
	v_mfma_f32_16x16x32_bf16 v[64:67], v[216:219], v[112:115], v[64:67]
	v_mfma_f32_16x16x32_bf16 v[72:75], v[216:219], v[136:139], v[72:75]
	ds_read_b128 v[216:219], v213 offset:39040
	s_waitcnt lgkmcnt(3)
	v_mfma_f32_16x16x32_bf16 v[64:67], v[224:227], v[116:119], v[64:67]
	v_mfma_f32_16x16x32_bf16 v[72:75], v[224:227], v[140:143], v[72:75]
	ds_read_b128 v[224:227], v214 offset:39040
	s_waitcnt lgkmcnt(3)
	v_mfma_f32_16x16x32_bf16 v[68:71], v[240:243], v[96:99], 0
	v_mfma_f32_16x16x32_bf16 v[76:79], v[240:243], v[120:123], 0
	ds_read_b128 v[240:243], v213 offset:39168
	s_waitcnt lgkmcnt(3)
	v_mfma_f32_16x16x32_bf16 v[68:71], v[244:247], v[100:103], v[68:71]
	v_mfma_f32_16x16x32_bf16 v[76:79], v[244:247], v[124:127], v[76:79]
	ds_read_b128 v[244:247], v214 offset:39168
	s_waitcnt lgkmcnt(3)
	v_mfma_f32_16x16x32_bf16 v[68:71], v[216:219], v[104:107], v[68:71]
	v_mfma_f32_16x16x32_bf16 v[76:79], v[216:219], v[128:131], v[76:79]
	ds_read_b128 v[216:219], v213 offset:45056
	s_waitcnt lgkmcnt(3)
	v_mfma_f32_16x16x32_bf16 v[68:71], v[224:227], v[108:111], v[68:71]
	v_mfma_f32_16x16x32_bf16 v[76:79], v[224:227], v[132:135], v[76:79]
	ds_read_b128 v[224:227], v214 offset:45056
	s_waitcnt lgkmcnt(3)
	v_mfma_f32_16x16x32_bf16 v[68:71], v[240:243], v[112:115], v[68:71]
	v_lshl_add_u64 v[166:167], s[70:71], 0, v[158:159]
	s_add_i32 m0, s42, 0x2000
	s_nop 0
	global_load_lds_dwordx4 v[166:167], off
	v_mfma_f32_16x16x32_bf16 v[76:79], v[240:243], v[136:139], v[76:79]
	ds_read_b128 v[240:243], v213 offset:45184
	s_waitcnt lgkmcnt(3)
	v_mfma_f32_16x16x32_bf16 v[68:71], v[244:247], v[116:119], v[68:71]
	v_mfma_f32_16x16x32_bf16 v[76:79], v[244:247], v[140:143], v[76:79]
	ds_read_b128 v[244:247], v214 offset:45184
	s_cmp_eq_u32 s66, 0
	s_cbranch_scc1 .Latt_fast
	v_sub_f32_e32 v64, v64, v206
	v_sub_f32_e32 v65, v65, v206
	v_exp_f32_e32 v64, v64
	s_waitcnt lgkmcnt(3)
	v_mfma_f32_16x16x32_bf16 v[80:83], v[216:219], v[96:99], 0
	v_sub_f32_e32 v66, v66, v206
	v_exp_f32_e32 v65, v65
	v_sub_f32_e32 v67, v67, v206
	v_mfma_f32_16x16x32_bf16 v[88:91], v[216:219], v[120:123], 0
	ds_read_b128 v[216:219], v213 offset:45312
	v_exp_f32_e32 v66, v66
	v_subrev_f32_e32 v68, s66, v68
	v_exp_f32_e32 v67, v67
	s_waitcnt lgkmcnt(3)
	v_mfma_f32_16x16x32_bf16 v[80:83], v[224:227], v[100:103], v[80:83]
	v_add_f32_e32 v146, v64, v65
	v_subrev_f32_e32 v69, s66, v69
	v_exp_f32_e32 v68, v68
	v_mfma_f32_16x16x32_bf16 v[88:91], v[224:227], v[124:127], v[88:91]
	ds_read_b128 v[224:227], v214 offset:45312
	v_add_f32_e32 v146, v66, v146
	v_subrev_f32_e32 v70, s66, v70
	v_exp_f32_e32 v69, v69
	s_waitcnt lgkmcnt(3)
	v_mfma_f32_16x16x32_bf16 v[80:83], v[240:243], v[104:107], v[80:83]
	v_add_f32_e32 v146, v67, v146
	v_subrev_f32_e32 v71, s66, v71
	v_exp_f32_e32 v70, v70
	v_mfma_f32_16x16x32_bf16 v[88:91], v[240:243], v[128:131], v[88:91]
	ds_read_b128 v[240:243], v213 offset:51200
	v_add_f32_e32 v146, v68, v146
	v_exp_f32_e32 v71, v71
	s_waitcnt lgkmcnt(3)
	v_mfma_f32_16x16x32_bf16 v[80:83], v[244:247], v[108:111], v[80:83]
	v_add_f32_e32 v146, v69, v146
	v_add_f32_e32 v146, v70, v146
	v_mfma_f32_16x16x32_bf16 v[88:91], v[244:247], v[132:135], v[88:91]
	ds_read_b128 v[244:247], v214 offset:51200
	v_add_f32_e32 v146, v71, v146
	v_cvt_pk_bf16_f32 v64, v64, v65
	s_waitcnt lgkmcnt(3)
; __device__ __forceinline__ void expP(f32x16& p0, f32x16& p1, float MB) {
; #pragma unroll
;     for (int r = 0; r < 16; ++r) p0[r] = __builtin_amdgcn_exp2f(p0[r] - MB);
; #pragma unroll
;     for (int r = 0; r < 16; ++r) p1[r] = __builtin_amdgcn_exp2f(p1[r] - MB);
; }
; __device__ __forceinline__ void maskLast(f32x16& p0, f32x16& p1) {
; #pragma unroll
;     for (int r = 8; r < 16; ++r) p0[r] = 0.f;
; #pragma unroll
;     for (int r = 0; r < 16; ++r) p1[r] = 0.f;
; }
; __device__ __forceinline__ void finishP(const f32x16& p0, const f32x16& p1, float& l_reg, bf16x8& pa0, bf16x8& pa1, bf16x8& pa2, bf16x8& pa3) {
;     float ps = 0.f;
; #pragma unroll
;     for (int r = 0; r < 16; ++r) ps += p0[r];
; #pragma unroll
;     for (int r = 0; r < 16; ++r) ps += p1[r];
;     l_reg += ps;
;     ...
;     PK4(p0, 0, pa0); PK4(p0, 8, pa1); PK4(p1, 0, pa2); PK4(p1, 8, pa3);
;     ...
; }
	v_mfma_f32_16x16x32_bf16 v[80:83], v[216:219], v[112:115], v[80:83]
	v_cvt_pk_bf16_f32 v65, v66, v67
	v_cvt_pk_bf16_f32 v66, v68, v69
	v_mfma_f32_16x16x32_bf16 v[88:91], v[216:219], v[136:139], v[88:91]
	ds_read_b128 v[216:219], v213 offset:51328
	v_cvt_pk_bf16_f32 v67, v70, v71
	v_sub_f32_e32 v72, v72, v206
	ds_read_b128 v[68:71], v214 offset:51328
	s_waitcnt lgkmcnt(4)
	v_mfma_f32_16x16x32_bf16 v[80:83], v[224:227], v[116:119], v[80:83]
	v_sub_f32_e32 v73, v73, v206
	v_exp_f32_e32 v72, v72
	v_mfma_f32_16x16x32_bf16 v[88:91], v[224:227], v[140:143], v[88:91]
	ds_read_b128 v[224:227], v213 offset:51456
	v_sub_f32_e32 v74, v74, v206
	v_exp_f32_e32 v73, v73
	s_waitcnt lgkmcnt(4)
	v_mfma_f32_16x16x32_bf16 v[84:87], v[240:243], v[96:99], 0
	v_lshl_add_u64 v[166:167], s[70:71], 0, v[160:161]
	s_add_i32 m0, s42, 0x4000
	s_nop 0
	global_load_lds_dwordx4 v[166:167], off
	v_sub_f32_e32 v75, v75, v206
	v_exp_f32_e32 v74, v74
	v_mfma_f32_16x16x32_bf16 v[92:95], v[240:243], v[120:123], 0
	ds_read_b128 v[240:243], v214 offset:51456
	v_subrev_f32_e32 v76, s66, v76
	v_exp_f32_e32 v75, v75
	s_waitcnt lgkmcnt(4)
	v_mfma_f32_16x16x32_bf16 v[84:87], v[244:247], v[100:103], v[84:87]
	v_add_f32_e32 v148, v72, v73
	v_subrev_f32_e32 v77, s66, v77
	v_mfma_f32_16x16x32_bf16 v[92:95], v[244:247], v[124:127], v[92:95]
	ds_read_b64_tr_b16 v[244:245], v147 offset:0
	ds_read_b64_tr_b16 v[246:247], v147 offset:4096
	v_exp_f32_e32 v76, v76
	v_add_f32_e32 v148, v74, v148
	s_waitcnt lgkmcnt(5)
	v_mfma_f32_16x16x32_bf16 v[84:87], v[216:219], v[104:107], v[84:87]
	v_subrev_f32_e32 v78, s66, v78
	v_exp_f32_e32 v77, v77
	v_mfma_f32_16x16x32_bf16 v[92:95], v[216:219], v[128:131], v[92:95]
	ds_read_b64_tr_b16 v[216:217], v147 offset:256
	ds_read_b64_tr_b16 v[218:219], v147 offset:4352
	v_add_f32_e32 v148, v75, v148
	v_subrev_f32_e32 v79, s66, v79
	s_waitcnt lgkmcnt(6)
	v_mfma_f32_16x16x32_bf16 v[84:87], v[68:71], v[108:111], v[84:87]
	v_exp_f32_e32 v78, v78
	v_add_f32_e32 v148, v76, v148
	v_mfma_f32_16x16x32_bf16 v[92:95], v[68:71], v[132:135], v[92:95]
	ds_read_b64_tr_b16 v[68:69], v147 offset:512
	ds_read_b64_tr_b16 v[70:71], v147 offset:4608
	v_exp_f32_e32 v79, v79
	v_add_f32_e32 v148, v77, v148
	s_waitcnt lgkmcnt(7)
	v_mfma_f32_16x16x32_bf16 v[84:87], v[224:227], v[112:115], v[84:87]
	v_add_f32_e32 v148, v78, v148
	v_add_f32_e32 v148, v79, v148
	v_mfma_f32_16x16x32_bf16 v[92:95], v[224:227], v[136:139], v[92:95]
	ds_read_b64_tr_b16 v[224:225], v147 offset:768
	ds_read_b64_tr_b16 v[226:227], v147 offset:4864
	v_cvt_pk_bf16_f32 v72, v72, v73
	v_cvt_pk_bf16_f32 v73, v74, v75
	s_waitcnt lgkmcnt(8)
	v_mfma_f32_16x16x32_bf16 v[84:87], v[240:243], v[116:119], v[84:87]
	v_cvt_pk_bf16_f32 v74, v76, v77
	v_cvt_pk_bf16_f32 v75, v78, v79
	ds_read_b64_tr_b16 v[76:77], v147 offset:1024
	ds_read_b64_tr_b16 v[78:79], v147 offset:5120
	v_mfma_f32_16x16x32_bf16 v[92:95], v[240:243], v[140:143], v[92:95]
	ds_read_b64_tr_b16 v[240:241], v147 offset:1280
	ds_read_b64_tr_b16 v[242:243], v147 offset:5376
	v_subrev_f32_e32 v80, s66, v80
	v_subrev_f32_e32 v81, s66, v81
	v_exp_f32_e32 v80, v80
	v_subrev_f32_e32 v82, s66, v82
	s_waitcnt lgkmcnt(10)
	v_mfma_f32_16x16x32_bf16 v[0:3], v[64:67], v[244:247], v[0:3]
	v_exp_f32_e32 v81, v81
	v_subrev_f32_e32 v83, s66, v83
	v_exp_f32_e32 v82, v82
	v_add_f32_e32 v146, v80, v146
	v_mfma_f32_16x16x32_bf16 v[32:35], v[72:75], v[244:247], v[32:35]
	ds_read_b64_tr_b16 v[244:245], v147 offset:1536
	ds_read_b64_tr_b16 v[246:247], v147 offset:5632
	v_subrev_f32_e32 v84, s66, v84
	v_exp_f32_e32 v83, v83
	v_add_f32_e32 v146, v81, v146
	v_subrev_f32_e32 v85, s66, v85
	s_waitcnt lgkmcnt(10)
	v_mfma_f32_16x16x32_bf16 v[4:7], v[64:67], v[216:219], v[4:7]
	v_exp_f32_e32 v84, v84
	v_add_f32_e32 v146, v82, v146
	v_subrev_f32_e32 v86, s66, v86
	v_exp_f32_e32 v85, v85
	v_mfma_f32_16x16x32_bf16 v[36:39], v[72:75], v[216:219], v[36:39]
	ds_read_b64_tr_b16 v[216:217], v147 offset:1792
	ds_read_b64_tr_b16 v[218:219], v147 offset:5888
	v_add_f32_e32 v146, v83, v146
	v_subrev_f32_e32 v87, s66, v87
	v_exp_f32_e32 v86, v86
	v_add_f32_e32 v146, v84, v146
	s_waitcnt lgkmcnt(10)
	v_mfma_f32_16x16x32_bf16 v[8:11], v[64:67], v[68:71], v[8:11]
	v_lshl_add_u64 v[166:167], s[68:69], 0, v[162:163]
	s_mov_b32 m0, s43
	v_lshl_add_u64 v[166:167], v[166:167], 0, s[20:21]
	global_load_lds_dwordx4 v[166:167], off
	v_exp_f32_e32 v87, v87
	v_add_f32_e32 v146, v85, v146
	v_add_f32_e32 v146, v86, v146
	v_add_f32_e32 v146, v87, v146
	v_mfma_f32_16x16x32_bf16 v[40:43], v[72:75], v[68:71], v[40:43]
	ds_read_b64_tr_b16 v[68:69], v147 offset:8192
	ds_read_b64_tr_b16 v[70:71], v147 offset:12288
	v_cvt_pk_bf16_f32 v80, v80, v81
	v_cvt_pk_bf16_f32 v81, v82, v83
	v_cvt_pk_bf16_f32 v82, v84, v85
	v_cvt_pk_bf16_f32 v83, v86, v87
	s_waitcnt lgkmcnt(10)
	v_mfma_f32_16x16x32_bf16 v[12:15], v[64:67], v[224:227], v[12:15]
	v_add_f32_e32 v155, v155, v146
	v_subrev_f32_e32 v88, s66, v88
	v_subrev_f32_e32 v89, s66, v89
	v_exp_f32_e32 v88, v88
	ds_read_b64_tr_b16 v[84:85], v147 offset:8448
	ds_read_b64_tr_b16 v[86:87], v147 offset:12544
	v_mfma_f32_16x16x32_bf16 v[44:47], v[72:75], v[224:227], v[44:47]
	ds_read_b64_tr_b16 v[224:225], v147 offset:8704
	ds_read_b64_tr_b16 v[226:227], v147 offset:12800
	v_subrev_f32_e32 v90, s66, v90
	v_exp_f32_e32 v89, v89
	v_subrev_f32_e32 v91, s66, v91
	v_exp_f32_e32 v90, v90
	s_waitcnt lgkmcnt(12)
	v_mfma_f32_16x16x32_bf16 v[16:19], v[64:67], v[76:79], v[16:19]
	v_add_f32_e32 v148, v88, v148
	v_subrev_f32_e32 v92, s66, v92
	v_exp_f32_e32 v91, v91
	v_add_f32_e32 v148, v89, v148
	v_mfma_f32_16x16x32_bf16 v[48:51], v[72:75], v[76:79], v[48:51]
	ds_read_b64_tr_b16 v[76:77], v147 offset:8960
	ds_read_b64_tr_b16 v[78:79], v147 offset:13056
	v_subrev_f32_e32 v93, s66, v93
	v_exp_f32_e32 v92, v92
	v_add_f32_e32 v148, v90, v148
	s_waitcnt lgkmcnt(12)
; #define SBAR() __builtin_amdgcn_sched_barrier(0)
; __device__ __forceinline__ void pv_d0(f32x16* o, int vb, bf16x8 pa0, bf16x8 pa1, bf16x8 pa2, bf16x8 pa3) {
;     VBlk A, B;
;     pv_load<0>(A, vb); pv_load<1>(B, vb);
;     asm volatile("s_waitcnt lgkmcnt(8)" ::: "memory"); SBAR(); pv_mma(o[0], A, pa0, pa1, pa2, pa3); SBAR();
;     pv_load<2>(A, vb);
;     asm volatile("s_waitcnt lgkmcnt(8)" ::: "memory"); SBAR(); pv_mma(o[1], B, pa0, pa1, pa2, pa3); SBAR();
;     pv_load<3>(B, vb);
;     asm volatile("s_waitcnt lgkmcnt(8)" ::: "memory"); SBAR(); pv_mma(o[2], A, pa0, pa1, pa2, pa3); SBAR();
;     asm volatile("s_waitcnt lgkmcnt(0)" ::: "memory"); SBAR(); pv_mma(o[3], B, pa0, pa1, pa2, pa3); SBAR();
; }
; __device__ __forceinline__ void attn_unit(const bf16_t* __restrict__ Qb, const bf16_t* __restrict__ Kh, const bf16_t* __restrict__ Vh, bf16_t* __restrict__ Ob,
;                                           LAS unsigned char* lds, float MB, int tid, int nrows, int t0, int t1, float* part, float* partl) {
;     ...
;     f32x16 p0, p1; bf16x8 pa0, pa1, pa2, pa3;
;     SDMA(t0 * KVBLK, 0); asm volatile("s_waitcnt vmcnt(0)" ::: "memory"); __syncthreads();
;     for (int j = t0; j < t1; ++j) {
;         const int b = (j - t0) & 1; const bool more = (j + 1 < t1);
;         if (more) { if (b) SDMA((j + 1) * KVBLK, 0); else SDMA((j + 1) * KVBLK, 1); }
	v_mfma_f32_16x16x32_bf16 v[20:23], v[64:67], v[240:243], v[20:23]
	v_subrev_f32_e32 v94, s66, v94
	v_exp_f32_e32 v93, v93
	v_add_f32_e32 v148, v91, v148
	v_mfma_f32_16x16x32_bf16 v[52:55], v[72:75], v[240:243], v[52:55]
	ds_read_b64_tr_b16 v[240:241], v147 offset:9216
	ds_read_b64_tr_b16 v[242:243], v147 offset:13312
	v_subrev_f32_e32 v95, s66, v95
	v_exp_f32_e32 v94, v94
	v_add_f32_e32 v148, v92, v148
	s_waitcnt lgkmcnt(12)
	v_mfma_f32_16x16x32_bf16 v[24:27], v[64:67], v[244:247], v[24:27]
	v_exp_f32_e32 v95, v95
	v_add_f32_e32 v148, v93, v148
	v_add_f32_e32 v148, v94, v148
	v_mfma_f32_16x16x32_bf16 v[56:59], v[72:75], v[244:247], v[56:59]
	ds_read_b64_tr_b16 v[244:245], v147 offset:9472
	ds_read_b64_tr_b16 v[246:247], v147 offset:13568
	v_add_f32_e32 v148, v95, v148
	v_cvt_pk_bf16_f32 v88, v88, v89
	v_cvt_pk_bf16_f32 v89, v90, v91
	s_waitcnt lgkmcnt(12)
	v_mfma_f32_16x16x32_bf16 v[28:31], v[64:67], v[216:219], v[28:31]
	v_cvt_pk_bf16_f32 v90, v92, v93
	v_cvt_pk_bf16_f32 v91, v94, v95
	v_add_f32_e32 v149, v149, v148
	ds_read_b64_tr_b16 v[92:93], v147 offset:9728
	ds_read_b64_tr_b16 v[94:95], v147 offset:13824
	v_mfma_f32_16x16x32_bf16 v[60:63], v[72:75], v[216:219], v[60:63]
	s_waitcnt lgkmcnt(12)
	v_mfma_f32_16x16x32_bf16 v[0:3], v[80:83], v[68:71], v[0:3]
	v_mfma_f32_16x16x32_bf16 v[32:35], v[88:91], v[68:71], v[32:35]
	ds_read_b64_tr_b16 v[216:217], v147 offset:9984
	ds_read_b64_tr_b16 v[218:219], v147 offset:14080
	s_waitcnt lgkmcnt(12)
	v_mfma_f32_16x16x32_bf16 v[4:7], v[80:83], v[84:87], v[4:7]
	v_mfma_f32_16x16x32_bf16 v[36:39], v[88:91], v[84:87], v[36:39]
	s_waitcnt lgkmcnt(10)
	v_mfma_f32_16x16x32_bf16 v[8:11], v[80:83], v[224:227], v[8:11]
	v_lshl_add_u64 v[166:167], s[68:69], 0, v[164:165]
	s_add_i32 m0, s43, 0x2000
	v_lshl_add_u64 v[166:167], v[166:167], 0, s[20:21]
	global_load_lds_dwordx4 v[166:167], off
	v_mfma_f32_16x16x32_bf16 v[40:43], v[88:91], v[224:227], v[40:43]
	s_waitcnt lgkmcnt(8)
	v_mfma_f32_16x16x32_bf16 v[12:15], v[80:83], v[76:79], v[12:15]
	v_mfma_f32_16x16x32_bf16 v[44:47], v[88:91], v[76:79], v[44:47]
	s_waitcnt lgkmcnt(6)
	v_mfma_f32_16x16x32_bf16 v[16:19], v[80:83], v[240:243], v[16:19]
	v_mfma_f32_16x16x32_bf16 v[48:51], v[88:91], v[240:243], v[48:51]
	s_waitcnt lgkmcnt(4)
	v_mfma_f32_16x16x32_bf16 v[20:23], v[80:83], v[244:247], v[20:23]
	v_mfma_f32_16x16x32_bf16 v[52:55], v[88:91], v[244:247], v[52:55]
	s_waitcnt lgkmcnt(2)
	v_mfma_f32_16x16x32_bf16 v[24:27], v[80:83], v[92:95], v[24:27]
	v_mfma_f32_16x16x32_bf16 v[56:59], v[88:91], v[92:95], v[56:59]
	s_waitcnt lgkmcnt(0)
	v_mfma_f32_16x16x32_bf16 v[28:31], v[80:83], v[216:219], v[28:31]
	v_mfma_f32_16x16x32_bf16 v[60:63], v[88:91], v[216:219], v[60:63]
	s_mov_b32 s71, 1
	s_branch .LBB0_137
.Latt_first:
	s_add_i32 s42, s66, 1
	s_cmp_ge_i32 s42, s47
	s_cbranch_scc1 .Latt_st2
	s_add_i32 s67, s52, 0
	s_lshl_b32 s68, s67, 13
	s_mov_b32 s69, 0
	s_mul_i32 s43, s67, 0x1800
	s_add_u32 s70, s54, s43
	s_addc_u32 s71, s55, 0
	s_add_u32 s68, s56, s68
	s_addc_u32 s69, s57, s69
	s_add_i32 s53, s65, 1
	s_cmp_ge_u32 s53, 3
	s_cselect_b32 s42, 3, 0
	s_sub_i32 s53, s53, s42
	s_cmp_eq_u32 s53, 2
	s_cselect_b32 s42, 0x5000, 0
	s_cselect_b32 s43, 0xd000, 0
	s_mul_i32 s67, s53, 0x6000
	s_add_i32 s42, s42, s67
	s_add_i32 s42, s42, 0x8000
	s_add_i32 s42, s58, s42
	s_lshl_b32 s67, s53, 14
	s_add_i32 s43, s43, s67
	s_add_i32 s43, s58, s43
	v_lshl_add_u64 v[64:65], s[70:71], 0, v[156:157]
	v_lshl_add_u64 v[66:67], s[70:71], 0, v[158:159]
	v_lshl_add_u64 v[68:69], s[70:71], 0, v[160:161]
	v_lshl_add_u64 v[70:71], s[68:69], 0, v[162:163]
	v_lshl_add_u64 v[72:73], s[68:69], 0, v[164:165]
	v_lshl_add_u64 v[70:71], v[70:71], 0, s[20:21]
	v_lshl_add_u64 v[72:73], v[72:73], 0, s[20:21]
	s_mov_b32 m0, s42
	s_nop 0
	global_load_lds_dwordx4 v[64:65], off
	s_add_i32 m0, s42, 0x2000
	s_nop 0
	global_load_lds_dwordx4 v[66:67], off
	s_add_i32 m0, s42, 0x4000
	s_nop 0
	global_load_lds_dwordx4 v[68:69], off
	s_mov_b32 m0, s43
	s_nop 0
	global_load_lds_dwordx4 v[70:71], off
	s_add_i32 m0, s43, 0x2000
	s_nop 0
	global_load_lds_dwordx4 v[72:73], off
	s_branch .Latt_st2
.Latt_inactive:
	s_add_i32 s42, s66, 2
	s_cmp_ge_i32 s42, s47
	s_cbranch_scc1 .Latt_in_none
	s_add_i32 s67, s52, 64
	s_lshl_b32 s68, s67, 13
	s_mov_b32 s69, 0
	s_mul_i32 s43, s67, 0x1800
	s_add_u32 s70, s54, s43
	s_addc_u32 s71, s55, 0
	s_add_u32 s68, s56, s68
	s_addc_u32 s69, s57, s69
	s_add_i32 s53, s65, 2
	s_cmp_ge_u32 s53, 3
	s_cselect_b32 s42, 3, 0
	s_sub_i32 s53, s53, s42
	s_cmp_eq_u32 s53, 2
	s_cselect_b32 s42, 0x5000, 0
	s_cselect_b32 s43, 0xd000, 0
	s_mul_i32 s67, s53, 0x6000
	s_add_i32 s42, s42, s67
	s_add_i32 s42, s42, 0x8000
	s_add_i32 s42, s58, s42
	s_lshl_b32 s67, s53, 14
	s_add_i32 s43, s43, s67
	s_add_i32 s43, s58, s43
	v_lshl_add_u64 v[64:65], s[70:71], 0, v[156:157]
	v_lshl_add_u64 v[66:67], s[70:71], 0, v[158:159]
	v_lshl_add_u64 v[68:69], s[70:71], 0, v[160:161]
	v_lshl_add_u64 v[70:71], s[68:69], 0, v[162:163]
	v_lshl_add_u64 v[72:73], s[68:69], 0, v[164:165]
	v_lshl_add_u64 v[70:71], v[70:71], 0, s[20:21]
	v_lshl_add_u64 v[72:73], v[72:73], 0, s[20:21]
	s_mov_b32 m0, s42
	s_nop 0
	global_load_lds_dwordx4 v[64:65], off
	s_add_i32 m0, s42, 0x2000
	s_nop 0
	global_load_lds_dwordx4 v[66:67], off
	s_add_i32 m0, s42, 0x4000
	s_nop 0
	global_load_lds_dwordx4 v[68:69], off
	s_mov_b32 m0, s43
	s_nop 0
	global_load_lds_dwordx4 v[70:71], off
	s_add_i32 m0, s43, 0x2000
	s_nop 0
	global_load_lds_dwordx4 v[72:73], off
	s_mov_b32 s71, 1
	s_branch .LBB0_137
.Latt_in_none:
	s_mov_b32 s71, 0
	s_branch .LBB0_137

; __device__ __forceinline__ void epi8(const Desc& d, int pb, int row, int col, f32x4 v0, f32x4 v1) {
;     ...
;     } else {
;         float* hp = (float*)d.o0 + (size_t)row * DM + col;
;         const float* rp = (row < LREAL ? (const float*)d.o2 + (size_t)row * DM : (const float*)d.gate + (size_t)(row - LREAL) * DM) + col;
;         v0 += *(const f32x4*)rp; v1 += *(const f32x4*)(rp + 4);
;         if (d.epi == EPI_RESID) { *(f32x4*)hp = v0; *(f32x4*)(hp + 4) = v1; }
;         else if (row < LREAL) { float* op = (float*)d.o1 + (size_t)row * DM + col; *(f32x4*)op = v0; *(f32x4*)(op + 4) = v1; }
;     }
; }
; __device__ __forceinline__ void epilogue(const Desc& d, const f32x4 (&acc)[2][2][4][2], const Unit& u, int wr, int wc, int fr, int fq) {
;     const int row0 = u.pm * BM + wr * 64 + fr, col0 = u.pn * BM + wc * 32 + 8 * fq;
; #pragma unroll
;     for (int ai = 0; ai < 2; ++ai)
; #pragma unroll
;         for (int m = 0; m < 4; ++m) {
; #pragma unroll
;             for (int bj = 0; bj < 2; ++bj) epi8(d, u.pb, row0 + ai * HALF + m * 16, col0 + bj * HALF, acc[ai][bj][m][0], acc[ai][bj][m][1]);
;             asm volatile("" ::: "memory"); }
; }
.LBB0_313:
	v_lshl_add_u32 v158, s74, 8, v151
	s_cmp_gt_i32 s59, 20
	s_cselect_b64 s[40:41], -1, 0
	s_cmp_lg_u32 s59, 21
	v_ashrrev_i32_e32 v159, 31, v158
	v_mad_i64_i32 v[160:161], s[0:1], v158, s17, 0
	v_add_u32_e32 v128, 0xffffe000, v158
	v_mov_b32_e32 v129, v145
	v_lshl_or_b32 v144, s59, 8, v171
	s_cselect_b64 s[72:73], -1, 0
	v_lshlrev_b64 v[162:163], 11, v[158:159]
	v_cmp_gt_i32_e64 s[0:1], s19, v158
	v_lshlrev_b64 v[164:165], 13, v[128:129]
	s_cmp_gt_i32 s26, 4
	s_cbranch_scc0 .Lepi_generic
	v_ashrrev_i32_e32 v189, 31, v144
	v_mov_b32_e32 v188, v144
	v_lshl_add_u64 v[182:183], v[162:163], 2, s[86:87]
	v_lshl_add_u64 v[182:183], v[188:189], 2, v[182:183]
	s_cmp_lg_u64 s[64:65], 0
	s_cselect_b64 s[74:75], s[84:85], s[50:51]
	v_lshl_add_u64 v[184:185], v[162:163], 2, s[74:75]
	v_lshl_add_u64 v[184:185], v[188:189], 2, v[184:185]
	v_mov_b32_e32 v191, 0
	v_mov_b32_e32 v190, 0x0
	v_lshl_add_u64 v[186:187], v[190:191], 0, v[182:183]
	global_load_dwordx4 v[192:195], v[186:187], off
	global_load_dwordx4 v[196:199], v[186:187], off offset:16
	v_mov_b32_e32 v190, 0x0
	v_lshl_add_u64 v[186:187], v[190:191], 0, v[182:183]
	global_load_dwordx4 v[206:209], v[186:187], off offset:512
	global_load_dwordx4 v[210:213], v[186:187], off offset:528
	s_waitcnt vmcnt(2)
	v_pk_add_f32 v[192:193], v[124:125], v[192:193]
	v_pk_add_f32 v[194:195], v[126:127], v[194:195]
	v_pk_add_f32 v[196:197], v[120:121], v[196:197]
	v_pk_add_f32 v[198:199], v[122:123], v[198:199]
	v_mov_b32_e32 v190, 0x0
	v_lshl_add_u64 v[188:189], v[190:191], 0, v[184:185]
	global_store_dwordx4 v[188:189], v[192:195], off
	global_store_dwordx4 v[188:189], v[196:199], off offset:16
	v_mov_b32_e32 v190, 0x20000
	v_lshl_add_u64 v[186:187], v[190:191], 0, v[182:183]
	global_load_dwordx4 v[120:123], v[186:187], off
	global_load_dwordx4 v[124:127], v[186:187], off offset:16
	s_waitcnt vmcnt(4)
	v_pk_add_f32 v[206:207], v[116:117], v[206:207]
	v_pk_add_f32 v[208:209], v[118:119], v[208:209]
	v_pk_add_f32 v[210:211], v[112:113], v[210:211]
	v_pk_add_f32 v[212:213], v[114:115], v[212:213]
	v_mov_b32_e32 v190, 0x0
	v_lshl_add_u64 v[188:189], v[190:191], 0, v[184:185]
	global_store_dwordx4 v[188:189], v[206:209], off offset:512
	global_store_dwordx4 v[188:189], v[210:213], off offset:528
	v_mov_b32_e32 v190, 0x20000
	v_lshl_add_u64 v[186:187], v[190:191], 0, v[182:183]
	global_load_dwordx4 v[112:115], v[186:187], off offset:512
	global_load_dwordx4 v[116:119], v[186:187], off offset:528
	s_waitcnt vmcnt(4)
	v_pk_add_f32 v[120:121], v[108:109], v[120:121]
	v_pk_add_f32 v[122:123], v[110:111], v[122:123]
	v_pk_add_f32 v[124:125], v[104:105], v[124:125]
	v_pk_add_f32 v[126:127], v[106:107], v[126:127]
	v_mov_b32_e32 v190, 0x20000
	v_lshl_add_u64 v[188:189], v[190:191], 0, v[184:185]
	global_store_dwordx4 v[188:189], v[120:123], off
	global_store_dwordx4 v[188:189], v[124:127], off offset:16
	v_mov_b32_e32 v190, 0x40000
	v_lshl_add_u64 v[186:187], v[190:191], 0, v[182:183]
	global_load_dwordx4 v[104:107], v[186:187], off
	global_load_dwordx4 v[108:111], v[186:187], off offset:16
	s_waitcnt vmcnt(4)
	v_pk_add_f32 v[112:113], v[100:101], v[112:113]
	v_pk_add_f32 v[114:115], v[102:103], v[114:115]
	v_pk_add_f32 v[116:117], v[96:97], v[116:117]
	v_pk_add_f32 v[118:119], v[98:99], v[118:119]
	v_mov_b32_e32 v190, 0x20000
	v_lshl_add_u64 v[188:189], v[190:191], 0, v[184:185]
	global_store_dwordx4 v[188:189], v[112:115], off offset:512
	global_store_dwordx4 v[188:189], v[116:119], off offset:528
	v_mov_b32_e32 v190, 0x40000
	v_lshl_add_u64 v[186:187], v[190:191], 0, v[182:183]
	global_load_dwordx4 v[96:99], v[186:187], off offset:512
	global_load_dwordx4 v[100:103], v[186:187], off offset:528
	s_waitcnt vmcnt(4)
	v_pk_add_f32 v[104:105], v[92:93], v[104:105]
	v_pk_add_f32 v[106:107], v[94:95], v[106:107]
	v_pk_add_f32 v[108:109], v[88:89], v[108:109]
	v_pk_add_f32 v[110:111], v[90:91], v[110:111]
	v_mov_b32_e32 v190, 0x40000
	v_lshl_add_u64 v[188:189], v[190:191], 0, v[184:185]
	global_store_dwordx4 v[188:189], v[104:107], off
	global_store_dwordx4 v[188:189], v[108:111], off offset:16
	v_mov_b32_e32 v190, 0x60000
	v_lshl_add_u64 v[186:187], v[190:191], 0, v[182:183]
	global_load_dwordx4 v[88:91], v[186:187], off
	global_load_dwordx4 v[92:95], v[186:187], off offset:16
	s_waitcnt vmcnt(4)
	v_pk_add_f32 v[96:97], v[84:85], v[96:97]
	v_pk_add_f32 v[98:99], v[86:87], v[98:99]
	v_pk_add_f32 v[100:101], v[80:81], v[100:101]
	v_pk_add_f32 v[102:103], v[82:83], v[102:103]
	v_mov_b32_e32 v190, 0x40000
	v_lshl_add_u64 v[188:189], v[190:191], 0, v[184:185]
	global_store_dwordx4 v[188:189], v[96:99], off offset:512
	global_store_dwordx4 v[188:189], v[100:103], off offset:528
	v_mov_b32_e32 v190, 0x60000
	v_lshl_add_u64 v[186:187], v[190:191], 0, v[182:183]
	global_load_dwordx4 v[80:83], v[186:187], off offset:512
	global_load_dwordx4 v[84:87], v[186:187], off offset:528
	s_waitcnt vmcnt(4)
; __device__ __forceinline__ void epi8(const Desc& d, int pb, int row, int col, f32x4 v0, f32x4 v1) {
;     ...
;         float* hp = (float*)d.o0 + (size_t)row * DM + col;
;         const float* rp = (row < LREAL ? (const float*)d.o2 + (size_t)row * DM : (const float*)d.gate + (size_t)(row - LREAL) * DM) + col;
;         v0 += *(const f32x4*)rp; v1 += *(const f32x4*)(rp + 4);
;         if (d.epi == EPI_RESID) { *(f32x4*)hp = v0; *(f32x4*)(hp + 4) = v1; }
;         else if (row < LREAL) { float* op = (float*)d.o1 + (size_t)row * DM + col; *(f32x4*)op = v0; *(f32x4*)(op + 4) = v1; }
; __device__ __forceinline__ void epilogue(const Desc& d, const f32x4 (&acc)[2][2][4][2], const Unit& u, int wr, int wc, int fr, int fq) {
;     ...
;     for (int ai = 0; ai < 2; ++ai)
; #pragma unroll
;         for (int m = 0; m < 4; ++m) {
; #pragma unroll
;             for (int bj = 0; bj < 2; ++bj) epi8(d, u.pb, row0 + ai * HALF + m * 16, col0 + bj * HALF, acc[ai][bj][m][0], acc[ai][bj][m][1]);
	v_pk_add_f32 v[88:89], v[76:77], v[88:89]
	v_pk_add_f32 v[90:91], v[78:79], v[90:91]
	v_pk_add_f32 v[92:93], v[72:73], v[92:93]
	v_pk_add_f32 v[94:95], v[74:75], v[94:95]
	v_mov_b32_e32 v190, 0x60000
	v_lshl_add_u64 v[188:189], v[190:191], 0, v[184:185]
	global_store_dwordx4 v[188:189], v[88:91], off
	global_store_dwordx4 v[188:189], v[92:95], off offset:16
	v_mov_b32_e32 v190, 0x100000
	v_lshl_add_u64 v[186:187], v[190:191], 0, v[182:183]
	global_load_dwordx4 v[72:75], v[186:187], off
	global_load_dwordx4 v[76:79], v[186:187], off offset:16
	s_waitcnt vmcnt(4)
	v_pk_add_f32 v[80:81], v[68:69], v[80:81]
	v_pk_add_f32 v[82:83], v[70:71], v[82:83]
	v_pk_add_f32 v[84:85], v[64:65], v[84:85]
	v_pk_add_f32 v[86:87], v[66:67], v[86:87]
	v_mov_b32_e32 v190, 0x60000
	v_lshl_add_u64 v[188:189], v[190:191], 0, v[184:185]
	global_store_dwordx4 v[188:189], v[80:83], off offset:512
	global_store_dwordx4 v[188:189], v[84:87], off offset:528
	v_mov_b32_e32 v190, 0x100000
	v_lshl_add_u64 v[186:187], v[190:191], 0, v[182:183]
	global_load_dwordx4 v[64:67], v[186:187], off offset:512
	global_load_dwordx4 v[68:71], v[186:187], off offset:528
	s_waitcnt vmcnt(4)
	v_pk_add_f32 v[72:73], v[60:61], v[72:73]
	v_pk_add_f32 v[74:75], v[62:63], v[74:75]
	v_pk_add_f32 v[76:77], v[56:57], v[76:77]
	v_pk_add_f32 v[78:79], v[58:59], v[78:79]
	v_mov_b32_e32 v190, 0x100000
	v_lshl_add_u64 v[188:189], v[190:191], 0, v[184:185]
	global_store_dwordx4 v[188:189], v[72:75], off
	global_store_dwordx4 v[188:189], v[76:79], off offset:16
	v_mov_b32_e32 v190, 0x120000
	v_lshl_add_u64 v[186:187], v[190:191], 0, v[182:183]
	global_load_dwordx4 v[56:59], v[186:187], off
	global_load_dwordx4 v[60:63], v[186:187], off offset:16
	s_waitcnt vmcnt(4)
	v_pk_add_f32 v[64:65], v[52:53], v[64:65]
	v_pk_add_f32 v[66:67], v[54:55], v[66:67]
	v_pk_add_f32 v[68:69], v[48:49], v[68:69]
	v_pk_add_f32 v[70:71], v[50:51], v[70:71]
	v_mov_b32_e32 v190, 0x100000
	v_lshl_add_u64 v[188:189], v[190:191], 0, v[184:185]
	global_store_dwordx4 v[188:189], v[64:67], off offset:512
	global_store_dwordx4 v[188:189], v[68:71], off offset:528
	v_mov_b32_e32 v190, 0x120000
	v_lshl_add_u64 v[186:187], v[190:191], 0, v[182:183]
	global_load_dwordx4 v[48:51], v[186:187], off offset:512
	global_load_dwordx4 v[52:55], v[186:187], off offset:528
	s_waitcnt vmcnt(4)
	v_pk_add_f32 v[56:57], v[44:45], v[56:57]
	v_pk_add_f32 v[58:59], v[46:47], v[58:59]
	v_pk_add_f32 v[60:61], v[40:41], v[60:61]
	v_pk_add_f32 v[62:63], v[42:43], v[62:63]
	v_mov_b32_e32 v190, 0x120000
	v_lshl_add_u64 v[188:189], v[190:191], 0, v[184:185]
	global_store_dwordx4 v[188:189], v[56:59], off
	global_store_dwordx4 v[188:189], v[60:63], off offset:16
	v_mov_b32_e32 v190, 0x140000
	v_lshl_add_u64 v[186:187], v[190:191], 0, v[182:183]
	global_load_dwordx4 v[40:43], v[186:187], off
	global_load_dwordx4 v[44:47], v[186:187], off offset:16
	s_waitcnt vmcnt(4)
	v_pk_add_f32 v[48:49], v[36:37], v[48:49]
	v_pk_add_f32 v[50:51], v[38:39], v[50:51]
	v_pk_add_f32 v[52:53], v[32:33], v[52:53]
	v_pk_add_f32 v[54:55], v[34:35], v[54:55]
	v_mov_b32_e32 v190, 0x120000
	v_lshl_add_u64 v[188:189], v[190:191], 0, v[184:185]
	global_store_dwordx4 v[188:189], v[48:51], off offset:512
	global_store_dwordx4 v[188:189], v[52:55], off offset:528
	v_mov_b32_e32 v190, 0x140000
	v_lshl_add_u64 v[186:187], v[190:191], 0, v[182:183]
	global_load_dwordx4 v[32:35], v[186:187], off offset:512
	global_load_dwordx4 v[36:39], v[186:187], off offset:528
	s_waitcnt vmcnt(4)
	v_pk_add_f32 v[40:41], v[28:29], v[40:41]
	v_pk_add_f32 v[42:43], v[30:31], v[42:43]
	v_pk_add_f32 v[44:45], v[24:25], v[44:45]
	v_pk_add_f32 v[46:47], v[26:27], v[46:47]
	v_mov_b32_e32 v190, 0x140000
	v_lshl_add_u64 v[188:189], v[190:191], 0, v[184:185]
	global_store_dwordx4 v[188:189], v[40:43], off
	global_store_dwordx4 v[188:189], v[44:47], off offset:16
	v_mov_b32_e32 v190, 0x160000
	v_lshl_add_u64 v[186:187], v[190:191], 0, v[182:183]
	global_load_dwordx4 v[24:27], v[186:187], off
	global_load_dwordx4 v[28:31], v[186:187], off offset:16
	s_waitcnt vmcnt(4)
	v_pk_add_f32 v[32:33], v[20:21], v[32:33]
	v_pk_add_f32 v[34:35], v[22:23], v[34:35]
	v_pk_add_f32 v[36:37], v[16:17], v[36:37]
	v_pk_add_f32 v[38:39], v[18:19], v[38:39]
	v_mov_b32_e32 v190, 0x140000
	v_lshl_add_u64 v[188:189], v[190:191], 0, v[184:185]
	global_store_dwordx4 v[188:189], v[32:35], off offset:512
	global_store_dwordx4 v[188:189], v[36:39], off offset:528
	v_mov_b32_e32 v190, 0x160000
	v_lshl_add_u64 v[186:187], v[190:191], 0, v[182:183]
	global_load_dwordx4 v[16:19], v[186:187], off offset:512
	global_load_dwordx4 v[20:23], v[186:187], off offset:528
	s_waitcnt vmcnt(4)
	v_pk_add_f32 v[24:25], v[12:13], v[24:25]
	v_pk_add_f32 v[26:27], v[14:15], v[26:27]
	v_pk_add_f32 v[28:29], v[8:9], v[28:29]
	v_pk_add_f32 v[30:31], v[10:11], v[30:31]
	v_mov_b32_e32 v190, 0x160000
	v_lshl_add_u64 v[188:189], v[190:191], 0, v[184:185]
	global_store_dwordx4 v[188:189], v[24:27], off
	global_store_dwordx4 v[188:189], v[28:31], off offset:16
	s_waitcnt vmcnt(2)
	v_pk_add_f32 v[16:17], v[0:1], v[16:17]
	v_pk_add_f32 v[18:19], v[2:3], v[18:19]
	v_pk_add_f32 v[20:21], v[4:5], v[20:21]
	v_pk_add_f32 v[22:23], v[6:7], v[22:23]
	v_mov_b32_e32 v190, 0x160000
	v_lshl_add_u64 v[188:189], v[190:191], 0, v[184:185]
	global_store_dwordx4 v[188:189], v[16:19], off offset:512
	global_store_dwordx4 v[188:189], v[20:23], off offset:528
	s_branch .LBB0_777

; __device__ __forceinline__ void skinny_phase(LAS unsigned char* lds, const Desc& g, int G, int bx, int wave, int lane) {
;     ...
;         for (int kk = 0; kk < ks; kk += 32) {
;             const bf16x8 af = *(const bf16x8*)(Ap + kk), w0 = *(const bf16x8*)(W0p + kk), w1 = *(const bf16x8*)(W1p + kk);
;             a0 = __builtin_amdgcn_mfma_f32_16x16x32_bf16(w0, af, a0, 0, 0, 0);
;             a1 = __builtin_amdgcn_mfma_f32_16x16x32_bf16(w1, af, a1, 0, 0, 0);
;         }
;         red[(wave * 64 + lane) * 2] = a0; red[(wave * 64 + lane) * 2 + 1] = a1;
;         __syncthreads();
;         if (wave == 0) {
; #pragma unroll
;             for (int w = 1; w < 8; ++w) { a0 += red[(w * 64 + lane) * 2]; a1 += red[(w * 64 + lane) * 2 + 1]; }
;             epi8(g, 0, LREAL + fr, c0 + 8 * fq, a0, a1);
.LBB0_823:
	global_load_dwordx4 v[38:41], v[34:35], off
	global_load_dwordx4 v[48:51], v[36:37], off
	global_load_dwordx4 v[56:59], v[32:33], off
	v_lshl_add_u64 v[34:35], v[34:35], 0, 64
	v_lshl_add_u64 v[36:37], v[36:37], 0, 64
	v_lshl_add_u64 v[32:33], v[32:33], 0, 64
.Lsk_top:
	s_add_i32 s8, s8, 32
	s_cmp_ge_u32 s8, s13
	s_cbranch_scc1 .Lsk_last_a
	global_load_dwordx4 v[60:63], v[34:35], off
	global_load_dwordx4 v[64:67], v[36:37], off
	global_load_dwordx4 v[68:71], v[32:33], off
	v_lshl_add_u64 v[34:35], v[34:35], 0, 64
	v_lshl_add_u64 v[36:37], v[36:37], 0, 64
	v_lshl_add_u64 v[32:33], v[32:33], 0, 64
	s_waitcnt vmcnt(3)
	v_mfma_f32_16x16x32_bf16 v[0:3], v[38:41], v[48:51], v[0:3]
	v_mfma_f32_16x16x32_bf16 v[4:7], v[56:59], v[48:51], v[4:7]
	s_add_i32 s8, s8, 32
	s_cmp_ge_u32 s8, s13
	s_cbranch_scc1 .Lsk_last_b
	global_load_dwordx4 v[38:41], v[34:35], off
	global_load_dwordx4 v[48:51], v[36:37], off
	global_load_dwordx4 v[56:59], v[32:33], off
	v_lshl_add_u64 v[34:35], v[34:35], 0, 64
	v_lshl_add_u64 v[36:37], v[36:37], 0, 64
	v_lshl_add_u64 v[32:33], v[32:33], 0, 64
	s_waitcnt vmcnt(3)
	v_mfma_f32_16x16x32_bf16 v[0:3], v[60:63], v[64:67], v[0:3]
	v_mfma_f32_16x16x32_bf16 v[4:7], v[68:71], v[64:67], v[4:7]
	s_branch .Lsk_top
.Lsk_last_a:
	s_waitcnt vmcnt(0)
	v_mfma_f32_16x16x32_bf16 v[0:3], v[38:41], v[48:51], v[0:3]
	v_mfma_f32_16x16x32_bf16 v[4:7], v[56:59], v[48:51], v[4:7]
	s_branch .Lsk_done
.Lsk_last_b:
	s_waitcnt vmcnt(0)
	v_mfma_f32_16x16x32_bf16 v[0:3], v[60:63], v[64:67], v[0:3]
	v_mfma_f32_16x16x32_bf16 v[4:7], v[68:71], v[64:67], v[4:7]
.Lsk_done:
	s_nop 7
	s_andn2_b64 vcc, exec, s[4:5]
	s_nop 1
	ds_write_b128 v9, v[0:3]
	s_nop 2
	ds_write_b128 v9, v[4:7] offset:16
	s_waitcnt lgkmcnt(0)
	s_barrier
	s_cbranch_vccnz .LBB0_821
	ds_read_b128 v[32:35], v44 offset:2048
	ds_read_b128 v[36:39], v44 offset:2064
	v_lshl_add_u32 v144, s6, 5, v8
	s_mov_b64 s[8:9], -1
	s_cmp_lt_i32 s26, 2
	s_waitcnt lgkmcnt(1)
	v_pk_add_f32 v[34:35], v[2:3], v[34:35]
	v_pk_add_f32 v[32:33], v[0:1], v[32:33]
	ds_read_b128 v[0:3], v44 offset:4096
	s_waitcnt lgkmcnt(1)
	v_pk_add_f32 v[6:7], v[6:7], v[38:39]
	v_pk_add_f32 v[4:5], v[4:5], v[36:37]
	s_waitcnt lgkmcnt(0)
	v_pk_add_f32 v[34:35], v[34:35], v[2:3]
	v_pk_add_f32 v[32:33], v[32:33], v[0:1]
	ds_read_b128 v[0:3], v44 offset:4112
	s_waitcnt lgkmcnt(0)
	v_pk_add_f32 v[6:7], v[6:7], v[2:3]
	v_pk_add_f32 v[4:5], v[4:5], v[0:1]
	ds_read_b128 v[0:3], v44 offset:6144
	s_waitcnt lgkmcnt(0)
	v_pk_add_f32 v[34:35], v[34:35], v[2:3]
	v_pk_add_f32 v[32:33], v[32:33], v[0:1]
	ds_read_b128 v[0:3], v44 offset:6160
	s_waitcnt lgkmcnt(0)
	v_pk_add_f32 v[6:7], v[6:7], v[2:3]
	v_pk_add_f32 v[4:5], v[4:5], v[0:1]
	ds_read_b128 v[0:3], v44 offset:8192
	s_waitcnt lgkmcnt(0)
	v_pk_add_f32 v[34:35], v[34:35], v[2:3]
	v_pk_add_f32 v[32:33], v[32:33], v[0:1]
	ds_read_b128 v[0:3], v44 offset:8208
	s_waitcnt lgkmcnt(0)
	v_pk_add_f32 v[6:7], v[6:7], v[2:3]
	v_pk_add_f32 v[4:5], v[4:5], v[0:1]
	ds_read_b128 v[0:3], v44 offset:10240
	s_waitcnt lgkmcnt(0)
	v_pk_add_f32 v[34:35], v[34:35], v[2:3]
	v_pk_add_f32 v[32:33], v[32:33], v[0:1]
	ds_read_b128 v[0:3], v44 offset:10256
	s_waitcnt lgkmcnt(0)
	v_pk_add_f32 v[6:7], v[6:7], v[2:3]
	v_pk_add_f32 v[4:5], v[4:5], v[0:1]
	ds_read_b128 v[0:3], v44 offset:12288
	s_waitcnt lgkmcnt(0)
	v_pk_add_f32 v[34:35], v[34:35], v[2:3]
	v_pk_add_f32 v[32:33], v[32:33], v[0:1]
	ds_read_b128 v[0:3], v44 offset:12304
	s_waitcnt lgkmcnt(0)
	v_pk_add_f32 v[6:7], v[6:7], v[2:3]
	v_pk_add_f32 v[36:37], v[4:5], v[0:1]
	ds_read_b128 v[2:5], v44 offset:14336
	s_waitcnt lgkmcnt(0)
	v_pk_add_f32 v[0:1], v[34:35], v[4:5]
	v_pk_add_f32 v[2:3], v[32:33], v[2:3]
	ds_read_b128 v[32:35], v44 offset:14352
	s_waitcnt lgkmcnt(0)
	v_pk_add_f32 v[4:5], v[6:7], v[34:35]
	v_pk_add_f32 v[6:7], v[36:37], v[32:33]
	s_cbranch_scc1 .LBB0_836
	s_cmp_lt_i32 s26, 5
	s_cbranch_scc1 .LBB0_830
	s_cmp_eq_u32 s26, 5
	s_cbranch_scc0 .LBB0_829
	v_ashrrev_i32_e32 v33, 31, v144
	v_mov_b32_e32 v32, v144
	v_lshlrev_b64 v[40:41], 2, v[32:33]
	v_lshl_add_u64 v[36:37], v[14:15], 0, v[40:41]
	flat_load_dwordx4 v[32:35], v[36:37] offset:16
	s_nop 0
	flat_load_dwordx4 v[36:39], v[36:37]
	v_lshl_add_u64 v[40:41], v[12:13], 0, v[40:41]
	s_waitcnt vmcnt(0) lgkmcnt(0)
	v_pk_add_f32 v[34:35], v[4:5], v[34:35]
	v_pk_add_f32 v[38:39], v[0:1], v[38:39]
	v_pk_add_f32 v[36:37], v[2:3], v[36:37]
	v_pk_add_f32 v[32:33], v[6:7], v[32:33]
	flat_store_dwordx4 v[40:41], v[36:39]
	flat_store_dwordx4 v[40:41], v[32:35] offset:16
